# G2->F seam: per-row-tile arrival counters, post-norm rows dealt tile-local, sample workgroups do not wait
# speedup vs baseline: 1.0176x; 1.0096x over previous
.LBB0_529:
	v_mbcnt_lo_u32_b32 v0, -1, 0
	v_mbcnt_hi_u32_b32 v0, -1, v0
	s_waitcnt vmcnt(0)
	s_waitcnt vmcnt(0)
	v_sub_u32_e32 v0, 0, v0
	v_cmp_eq_u32_e32 vcc, s3, v0
	s_barrier
	s_and_saveexec_b64 s[6:7], vcc
	s_cbranch_execz .LBB0_577
	s_and_b32 s16, s2, 7
	s_lshl_b32 s16, s16, 3
	s_bfe_u32 s17, s2, 0x30003
	s_or_b32 s16, s16, s17
	s_lshl_b32 s16, s16, 7
	s_add_u32 s16, s16, 0xf000040
	s_add_u32 s16, s10, s16
	s_addc_u32 s17, s11, 0
	v_mov_b32_e32 v1, 0
	v_mov_b32_e32 v2, 1
	global_atomic_add v1, v2, s[16:17]
	s_cmpk_lt_u32 s2, 0x40
	s_cbranch_scc1 .LBB0_577
	s_lshl_b32 s19, s28, 2
	s_add_i32 s19, s19, 4
	s_mov_b32 s20, 0x20000
.Lg2t_poll:
	global_load_dword v2, v1, s[16:17] sc1
	s_waitcnt vmcnt(0)
	v_readfirstlane_b32 s21, v2
	s_cmp_ge_u32 s21, s19
	s_cbranch_scc1 .Lg2t_seen
	s_sleep 2
	s_sub_u32 s20, s20, 1
	s_cmp_lg_u32 s20, 0
	s_cbranch_scc1 .Lg2t_poll
.Lg2t_seen:
	buffer_inv sc1
	s_waitcnt vmcnt(0)
.LBB0_577:
	s_or_b64 exec, exec, s[6:7]
	s_mov_b32 s6, s96
	s_waitcnt lgkmcnt(0)
	s_barrier
	s_cmpk_gt_i32 s6, 0x80
	s_mov_b64 s[6:7], -1
	s_cbranch_scc1 .LBB0_683
	s_mov_b32 s21, 0
	s_branch .LBB0_581

.LBB0_683:
	s_and_b64 vcc, exec, s[6:7]
	s_cbranch_vccz .LBB0_752
	v_readlane_b32 s16, v253, 38
	v_readlane_b32 s17, v253, 39
	s_mov_b64 s[6:7], -1
	s_and_b64 vcc, exec, s[16:17]
	s_cbranch_vccz .LBB0_701
	v_readlane_b32 s6, v252, 32
	v_readlane_b32 s7, v252, 33
	s_add_i32 s6, s6, s7
	s_cmpk_gt_i32 s6, 0x21ff
	v_mbcnt_lo_u32_b32 v16, -1, 0
	v_mbcnt_hi_u32_b32 v16, -1, v16
	s_cbranch_scc1 .LBB0_700
	s_lshl_b32 s68, s28, 10
	v_readlane_b32 s36, v252, 0
	s_lshl_b64 s[16:17], s[68:69], 2
	v_readlane_b32 s48, v252, 12
	v_lshlrev_b32_e32 v18, 3, v16
	v_readlane_b32 s49, v252, 13
	s_add_u32 s16, s48, s16
	v_ashrrev_i32_e32 v19, 31, v18
	s_addc_u32 s17, s49, s17
	v_lshlrev_b64 v[20:21], 2, v[18:19]
	v_lshl_add_u64 v[12:13], s[16:17], 0, v[20:21]
	global_load_dwordx4 v[0:3], v[12:13], off offset:2064
	global_load_dwordx4 v[4:7], v[12:13], off offset:2048
	global_load_dwordx4 v[8:11], v[12:13], off offset:16
	s_nop 0
	global_load_dwordx4 v[12:15], v[12:13], off
	s_and_b32 s6, s6, 7
	s_lshl_b32 s6, s6, 1
	s_lshr_b32 s7, s2, 6
	s_sub_i32 s7, s7, 1
	s_lshl_b32 s7, s7, 4
	s_add_i32 s6, s6, s7
	s_and_b32 s7, s2, 7
	s_lshl_b32 s7, s7, 3
	s_bfe_u32 s99, s2, 0x30003
	s_or_b32 s7, s7, s99
	s_lshl_b32 s7, s7, 8
	s_add_i32 s6, s6, s7
	s_or_b32 s99, s7, 0xff
	v_readlane_b32 s28, v255, 29
	v_readlane_b32 s38, v252, 2
	v_readlane_b32 s39, v252, 3
	s_cmp_lg_u32 s28, 3
	v_readlane_b32 s40, v252, 4
	v_readlane_b32 s41, v252, 5
	s_cselect_b64 s[38:39], -1, 0
	s_ashr_i32 s7, s6, 31
	s_lshl_b64 s[40:41], s[6:7], 2
	s_lshl_b64 s[16:17], s[6:7], 12
	v_readlane_b32 s21, v255, 3
	s_add_u32 s16, s21, s16
	v_readlane_b32 s21, v255, 4
	v_readlane_b32 s37, v252, 1
	v_lshlrev_b32_e32 v17, 2, v16
	s_addc_u32 s17, s21, s17
	v_xor_b32_e32 v56, 4, v17
	v_xor_b32_e32 v57, 8, v17
	v_xor_b32_e32 v58, 16, v17
	v_xor_b32_e32 v59, 32, v17
	v_xor_b32_e32 v60, 64, v17
	v_xor_b32_e32 v61, 0x80, v17
	v_cmp_eq_u32_e64 s[36:37], 0, v16
	v_lshl_add_u64 v[48:49], s[16:17], 0, v[20:21]
	s_lshl_b64 s[16:17], s[6:7], 11
	v_lshlrev_b64 v[16:17], 1, v[18:19]
	v_lshl_add_u64 v[50:51], s[16:17], 0, v[16:17]
	s_lshl_b64 s[16:17], s[6:7], 13
	v_lshl_add_u64 v[52:53], s[16:17], 0, v[16:17]
	v_readlane_b32 s42, v252, 6
	v_readlane_b32 s43, v252, 7
	v_readlane_b32 s44, v252, 8
	v_readlane_b32 s45, v252, 9
	v_readlane_b32 s46, v252, 10
	v_readlane_b32 s47, v252, 11
	v_readlane_b32 s50, v252, 14
	v_readlane_b32 s51, v252, 15
	v_readlane_b32 s29, v255, 30
	s_branch .LBB0_688
.LBB0_687:
	s_add_i32 s6, s6, 48
	s_add_u32 s40, s40, 0xc0
	s_addc_u32 s41, s41, 0
	s_mov_b32 s16, 0x30000
	s_mov_b32 s17, 0
	v_lshl_add_u64 v[48:49], v[48:49], 0, s[16:17]
	s_mov_b32 s16, 0x18000
	v_lshl_add_u64 v[50:51], v[50:51], 0, s[16:17]
	s_mov_b32 s16, 0x60000
	v_lshl_add_u64 v[52:53], v[52:53], 0, s[16:17]
	s_cmp_gt_i32 s6, s99
	s_cbranch_scc1 .LBB0_700
